# r19 + XCC-local workgroups poll their generation word back to back (s_sleep removed from the local spin too)
# baseline (speedup 1.0000x reference)
.Lgb_spin_s0:
	global_load_dword v1, v0, s[68:69] sc1
	s_waitcnt vmcnt(0)
	v_cmp_gt_u32_e32 vcc, s4, v1
	s_cbranch_vccz .Lgb_done_s0
	s_branch .Lgb_spin_s0
